# speedup vs baseline: 1.0029x; 1.0029x over previous
; #define RUNPH(n) { run_phase(p, (n), smem); grid.sync(); }
; __global__ void __launch_bounds__(256, 2) mega(Params p) {
;   extern __shared__ __attribute__((aligned(16))) char smem[];
;   cg::grid_group grid = cg::this_grid();
;   RUNPH(0) RUNPH(1) RUNPH(2) RUNPH(3) RUNPH(4) RUNPH(5) RUNPH(6) RUNPH(7) RUNPH(8)
.LBB0_169:
	s_waitcnt vmcnt(0)
	s_barrier
	s_mov_b64 s[4:5], exec
	v_readlane_b32 s0, v225, 14
	v_readlane_b32 s1, v225, 15
	s_and_b64 s[0:1], s[4:5], s[0:1]
	s_mov_b64 exec, s[0:1]
	s_cbranch_execz .LBB0_179
	buffer_wbl2 sc1
	s_waitcnt vmcnt(0)
	s_and_b32 s0, s98, 7
	s_sub_u32 s1, s99, s0
	s_add_u32 s1, s1, 7
	s_lshr_b32 s1, s1, 3
	s_mul_i32 s1, s1, 1
	s_lshl_b32 s0, s0, 8
	v_mov_b32_e32 v2, s0
	v_mov_b32_e32 v0, 0
	v_mov_b32_e32 v1, 1
	s_add_u32 s6, s30, 0x3eb38000
	s_addc_u32 s7, s31, 0
	s_mov_b32 s8, 0
	global_atomic_add v3, v2, v1, s[6:7] sc0
	s_waitcnt vmcnt(0)
	v_readfirstlane_b32 s0, v3
	s_add_u32 s0, s0, 1
	s_cmp_eq_u32 s0, s1
	s_cbranch_scc0 .Lgb1_pollg
	s_add_u32 s6, s6, 0x1000
	s_addc_u32 s7, s7, 0
	global_atomic_add v3, v0, v1, s[6:7] sc0
	s_min_u32 s1, s99, 8
	s_mul_i32 s1, s1, 1
	s_waitcnt vmcnt(0)
	v_readfirstlane_b32 s0, v3
	s_add_u32 s0, s0, 1
	s_cmp_eq_u32 s0, s1
	s_cbranch_scc0 .Lgb1_pollt
	global_atomic_add v0, v1, s[6:7] offset:256
	s_branch .Lgb1_relg

; #define RUNPH(n) { run_phase(p, (n), smem); grid.sync(); }
; __global__ void __launch_bounds__(256, 2) mega(Params p) {
;   extern __shared__ __attribute__((aligned(16))) char smem[];
;   cg::grid_group grid = cg::this_grid();
;   RUNPH(0) RUNPH(1) RUNPH(2) RUNPH(3) RUNPH(4) RUNPH(5) RUNPH(6) RUNPH(7) RUNPH(8)
.Lgb1_done:
	buffer_inv sc1
	s_waitcnt vmcnt(0)

; #define RUNPH(n) { run_phase(p, (n), smem); grid.sync(); }
; __global__ void __launch_bounds__(256, 2) mega(Params p) {
;   extern __shared__ __attribute__((aligned(16))) char smem[];
;   cg::grid_group grid = cg::this_grid();
;   RUNPH(0) RUNPH(1) RUNPH(2) RUNPH(3) RUNPH(4) RUNPH(5) RUNPH(6) RUNPH(7) RUNPH(8)
.LBB0_182:
	s_or_b64 exec, exec, s[18:19]
	s_waitcnt vmcnt(0)
	s_barrier
	s_mov_b64 s[4:5], exec
	v_readlane_b32 s0, v225, 14
	v_readlane_b32 s1, v225, 15
	s_and_b64 s[0:1], s[4:5], s[0:1]
	s_mov_b64 exec, s[0:1]
	s_cbranch_execz .LBB0_192
	buffer_wbl2 sc1
	s_waitcnt vmcnt(0)
	s_and_b32 s0, s98, 7
	s_sub_u32 s1, s99, s0
	s_add_u32 s1, s1, 7
	s_lshr_b32 s1, s1, 3
	s_mul_i32 s1, s1, 2
	s_lshl_b32 s0, s0, 8
	v_mov_b32_e32 v2, s0
	v_mov_b32_e32 v0, 0
	v_mov_b32_e32 v1, 1
	s_add_u32 s6, s30, 0x3eb38000
	s_addc_u32 s7, s31, 0
	s_mov_b32 s8, 0
	global_atomic_add v3, v2, v1, s[6:7] sc0
	s_waitcnt vmcnt(0)
	v_readfirstlane_b32 s0, v3
	s_add_u32 s0, s0, 1
	s_cmp_eq_u32 s0, s1
	s_cbranch_scc0 .Lgb2_pollg
	s_add_u32 s6, s6, 0x1000
	s_addc_u32 s7, s7, 0
	global_atomic_add v3, v0, v1, s[6:7] sc0
	s_min_u32 s1, s99, 8
	s_mul_i32 s1, s1, 2
	s_waitcnt vmcnt(0)
	v_readfirstlane_b32 s0, v3
	s_add_u32 s0, s0, 1
	s_cmp_eq_u32 s0, s1
	s_cbranch_scc0 .Lgb2_pollt
	global_atomic_add v0, v1, s[6:7] offset:256
	s_branch .Lgb2_relg

; #define RUNPH(n) { run_phase(p, (n), smem); grid.sync(); }
; __global__ void __launch_bounds__(256, 2) mega(Params p) {
;   extern __shared__ __attribute__((aligned(16))) char smem[];
;   cg::grid_group grid = cg::this_grid();
;   RUNPH(0) RUNPH(1) RUNPH(2) RUNPH(3) RUNPH(4) RUNPH(5) RUNPH(6) RUNPH(7) RUNPH(8)
.LBB0_205:
	s_waitcnt vmcnt(0)
	s_barrier
	s_mov_b64 s[4:5], exec
	v_readlane_b32 s0, v225, 14
	v_readlane_b32 s1, v225, 15
	s_and_b64 s[0:1], s[4:5], s[0:1]
	s_mov_b64 exec, s[0:1]
	s_cbranch_execz .LBB0_215
	buffer_wbl2 sc1
	s_waitcnt vmcnt(0)
	s_and_b32 s0, s98, 7
	s_sub_u32 s1, s99, s0
	s_add_u32 s1, s1, 7
	s_lshr_b32 s1, s1, 3
	s_mul_i32 s1, s1, 3
	s_lshl_b32 s0, s0, 8
	v_mov_b32_e32 v2, s0
	v_mov_b32_e32 v0, 0
	v_mov_b32_e32 v1, 1
	s_add_u32 s6, s30, 0x3eb38000
	s_addc_u32 s7, s31, 0
	s_mov_b32 s8, 0
	global_atomic_add v3, v2, v1, s[6:7] sc0
	s_waitcnt vmcnt(0)
	v_readfirstlane_b32 s0, v3
	s_add_u32 s0, s0, 1
	s_cmp_eq_u32 s0, s1
	s_cbranch_scc0 .Lgb3_pollg
	s_add_u32 s6, s6, 0x1000
	s_addc_u32 s7, s7, 0
	global_atomic_add v3, v0, v1, s[6:7] sc0
	s_min_u32 s1, s99, 8
	s_mul_i32 s1, s1, 3
	s_waitcnt vmcnt(0)
	v_readfirstlane_b32 s0, v3
	s_add_u32 s0, s0, 1
	s_cmp_eq_u32 s0, s1
	s_cbranch_scc0 .Lgb3_pollt
	global_atomic_add v0, v1, s[6:7] offset:256
	s_branch .Lgb3_relg

; #define RUNPH(n) { run_phase(p, (n), smem); grid.sync(); }
; __global__ void __launch_bounds__(256, 2) mega(Params p) {
;   extern __shared__ __attribute__((aligned(16))) char smem[];
;   cg::grid_group grid = cg::this_grid();
;   RUNPH(0) RUNPH(1) RUNPH(2) RUNPH(3) RUNPH(4) RUNPH(5) RUNPH(6) RUNPH(7) RUNPH(8)
.LBB0_252:
	s_waitcnt vmcnt(0)
	s_barrier
	s_mov_b64 s[4:5], exec
	v_readlane_b32 s0, v225, 14
	v_readlane_b32 s1, v225, 15
	s_and_b64 s[0:1], s[4:5], s[0:1]
	s_mov_b64 exec, s[0:1]
	s_cbranch_execz .LBB0_262
	buffer_wbl2 sc1
	s_waitcnt vmcnt(0)
	s_and_b32 s0, s98, 7
	s_sub_u32 s1, s99, s0
	s_add_u32 s1, s1, 7
	s_lshr_b32 s1, s1, 3
	s_mul_i32 s1, s1, 4
	s_lshl_b32 s0, s0, 8
	v_mov_b32_e32 v2, s0
	v_mov_b32_e32 v0, 0
	v_mov_b32_e32 v1, 1
	s_add_u32 s6, s30, 0x3eb38000
	s_addc_u32 s7, s31, 0
	s_mov_b32 s8, 0
	global_atomic_add v3, v2, v1, s[6:7] sc0
	s_waitcnt vmcnt(0)
	v_readfirstlane_b32 s0, v3
	s_add_u32 s0, s0, 1
	s_cmp_eq_u32 s0, s1
	s_cbranch_scc0 .Lgb4_pollg
	s_add_u32 s6, s6, 0x1000
	s_addc_u32 s7, s7, 0
	global_atomic_add v3, v0, v1, s[6:7] sc0
	s_min_u32 s1, s99, 8
	s_mul_i32 s1, s1, 4
	s_waitcnt vmcnt(0)
	v_readfirstlane_b32 s0, v3
	s_add_u32 s0, s0, 1
	s_cmp_eq_u32 s0, s1
	s_cbranch_scc0 .Lgb4_pollt
	global_atomic_add v0, v1, s[6:7] offset:256
	s_branch .Lgb4_relg

; #define RUNPH(n) { run_phase(p, (n), smem); grid.sync(); }
; __global__ void __launch_bounds__(256, 2) mega(Params p) {
;   extern __shared__ __attribute__((aligned(16))) char smem[];
;   cg::grid_group grid = cg::this_grid();
;   RUNPH(0) RUNPH(1) RUNPH(2) RUNPH(3) RUNPH(4) RUNPH(5) RUNPH(6) RUNPH(7) RUNPH(8)
.LBB0_317:
	s_waitcnt vmcnt(0)
	s_barrier
	s_mov_b64 s[4:5], exec
	v_readlane_b32 s0, v225, 14
	v_readlane_b32 s1, v225, 15
	s_and_b64 s[0:1], s[4:5], s[0:1]
	s_mov_b64 exec, s[0:1]
	s_cbranch_execz .LBB0_327
	buffer_wbl2 sc1
	s_waitcnt vmcnt(0)
	s_and_b32 s0, s98, 7
	s_sub_u32 s1, s99, s0
	s_add_u32 s1, s1, 7
	s_lshr_b32 s1, s1, 3
	s_mul_i32 s1, s1, 5
	s_lshl_b32 s0, s0, 8
	v_mov_b32_e32 v2, s0
	v_mov_b32_e32 v0, 0
	v_mov_b32_e32 v1, 1
	s_add_u32 s6, s30, 0x3eb38000
	s_addc_u32 s7, s31, 0
	s_mov_b32 s8, 0
	global_atomic_add v3, v2, v1, s[6:7] sc0
	s_waitcnt vmcnt(0)
	v_readfirstlane_b32 s0, v3
	s_add_u32 s0, s0, 1
	s_cmp_eq_u32 s0, s1
	s_cbranch_scc0 .Lgb5_pollg
	s_add_u32 s6, s6, 0x1000
	s_addc_u32 s7, s7, 0
	global_atomic_add v3, v0, v1, s[6:7] sc0
	s_min_u32 s1, s99, 8
	s_mul_i32 s1, s1, 5
	s_waitcnt vmcnt(0)
	v_readfirstlane_b32 s0, v3
	s_add_u32 s0, s0, 1
	s_cmp_eq_u32 s0, s1
	s_cbranch_scc0 .Lgb5_pollt
	global_atomic_add v0, v1, s[6:7] offset:256
	s_branch .Lgb5_relg

; #define RUNPH(n) { run_phase(p, (n), smem); grid.sync(); }
; __global__ void __launch_bounds__(256, 2) mega(Params p) {
;   extern __shared__ __attribute__((aligned(16))) char smem[];
;   cg::grid_group grid = cg::this_grid();
;   RUNPH(0) RUNPH(1) RUNPH(2) RUNPH(3) RUNPH(4) RUNPH(5) RUNPH(6) RUNPH(7) RUNPH(8)
.LBB0_390:
	s_waitcnt lgkmcnt(0)
	s_waitcnt vmcnt(0)
	s_barrier
	s_mov_b64 s[4:5], exec
	v_readlane_b32 s0, v225, 14
	v_readlane_b32 s1, v225, 15
	s_and_b64 s[0:1], s[4:5], s[0:1]
	s_mov_b64 exec, s[0:1]
	s_cbranch_execz .LBB0_400
	buffer_wbl2 sc1
	s_waitcnt vmcnt(0)
	s_and_b32 s0, s98, 7
	s_sub_u32 s1, s99, s0
	s_add_u32 s1, s1, 7
	s_lshr_b32 s1, s1, 3
	s_mul_i32 s1, s1, 6
	s_lshl_b32 s0, s0, 8
	v_mov_b32_e32 v2, s0
	v_mov_b32_e32 v0, 0
	v_mov_b32_e32 v1, 1
	s_add_u32 s6, s30, 0x3eb38000
	s_addc_u32 s7, s31, 0
	s_mov_b32 s8, 0
	global_atomic_add v3, v2, v1, s[6:7] sc0
	s_waitcnt vmcnt(0)
	v_readfirstlane_b32 s0, v3
	s_add_u32 s0, s0, 1
	s_cmp_eq_u32 s0, s1
	s_cbranch_scc0 .Lgb6_pollg
	s_add_u32 s6, s6, 0x1000
	s_addc_u32 s7, s7, 0
	global_atomic_add v3, v0, v1, s[6:7] sc0
	s_min_u32 s1, s99, 8
	s_mul_i32 s1, s1, 6
	s_waitcnt vmcnt(0)
	v_readfirstlane_b32 s0, v3
	s_add_u32 s0, s0, 1
	s_cmp_eq_u32 s0, s1
	s_cbranch_scc0 .Lgb6_pollt
	global_atomic_add v0, v1, s[6:7] offset:256
	s_branch .Lgb6_relg

; #define RUNPH(n) { run_phase(p, (n), smem); grid.sync(); }
; __global__ void __launch_bounds__(256, 2) mega(Params p) {
;   extern __shared__ __attribute__((aligned(16))) char smem[];
;   cg::grid_group grid = cg::this_grid();
;   RUNPH(0) RUNPH(1) RUNPH(2) RUNPH(3) RUNPH(4) RUNPH(5) RUNPH(6) RUNPH(7) RUNPH(8)
.LBB0_403:
	s_waitcnt vmcnt(0)
	s_barrier
	s_mov_b64 s[4:5], exec
	v_readlane_b32 s2, v225, 14
	v_readlane_b32 s3, v225, 15
	s_and_b64 s[2:3], s[4:5], s[2:3]
	v_readlane_b32 s34, v225, 2
	v_readlane_b32 s35, v225, 3
	s_mov_b64 exec, s[2:3]
	s_cbranch_execz .LBB0_413
	buffer_wbl2 sc1
	s_waitcnt vmcnt(0)
	s_and_b32 s2, s98, 7
	s_sub_u32 s3, s99, s2
	s_add_u32 s3, s3, 7
	s_lshr_b32 s3, s3, 3
	s_mul_i32 s3, s3, 7
	s_lshl_b32 s2, s2, 8
	v_mov_b32_e32 v2, s2
	v_mov_b32_e32 v0, 0
	v_mov_b32_e32 v1, 1
	s_add_u32 s6, s30, 0x3eb38000
	s_addc_u32 s7, s31, 0
	s_mov_b32 s8, 0
	global_atomic_add v3, v2, v1, s[6:7] sc0
	s_waitcnt vmcnt(0)
	v_readfirstlane_b32 s2, v3
	s_add_u32 s2, s2, 1
	s_cmp_eq_u32 s2, s3
	s_cbranch_scc0 .Lgb7_pollg
	s_add_u32 s6, s6, 0x1000
	s_addc_u32 s7, s7, 0
	global_atomic_add v3, v0, v1, s[6:7] sc0
	s_min_u32 s3, s99, 8
	s_mul_i32 s3, s3, 7
	s_waitcnt vmcnt(0)
	v_readfirstlane_b32 s2, v3
	s_add_u32 s2, s2, 1
	s_cmp_eq_u32 s2, s3
	s_cbranch_scc0 .Lgb7_pollt
	global_atomic_add v0, v1, s[6:7] offset:256
	s_branch .Lgb7_relg

; #define RUNPH(n) { run_phase(p, (n), smem); grid.sync(); }
; __global__ void __launch_bounds__(256, 2) mega(Params p) {
;   extern __shared__ __attribute__((aligned(16))) char smem[];
;   cg::grid_group grid = cg::this_grid();
;   RUNPH(0) RUNPH(1) RUNPH(2) RUNPH(3) RUNPH(4) RUNPH(5) RUNPH(6) RUNPH(7) RUNPH(8)
.LBB0_451:
	s_waitcnt vmcnt(0)
	s_barrier
	s_mov_b64 s[6:7], exec
	v_readlane_b32 s0, v225, 14
	v_readlane_b32 s1, v225, 15
	s_and_b64 s[0:1], s[6:7], s[0:1]
	s_mov_b64 exec, s[0:1]
	s_cbranch_execz .LBB0_461
	buffer_wbl2 sc1
	s_waitcnt vmcnt(0)
	s_and_b32 s0, s98, 7
	s_sub_u32 s1, s99, s0
	s_add_u32 s1, s1, 7
	s_lshr_b32 s1, s1, 3
	s_mul_i32 s1, s1, 8
	s_lshl_b32 s0, s0, 8
	v_mov_b32_e32 v2, s0
	v_mov_b32_e32 v0, 0
	v_mov_b32_e32 v1, 1
	s_add_u32 s8, s30, 0x3eb38000
	s_addc_u32 s9, s31, 0
	s_mov_b32 s10, 0
	global_atomic_add v3, v2, v1, s[8:9] sc0
	s_waitcnt vmcnt(0)
	v_readfirstlane_b32 s0, v3
	s_add_u32 s0, s0, 1
	s_cmp_eq_u32 s0, s1
	s_cbranch_scc0 .Lgb8_pollg
	s_add_u32 s8, s8, 0x1000
	s_addc_u32 s9, s9, 0
	global_atomic_add v3, v0, v1, s[8:9] sc0
	s_min_u32 s1, s99, 8
	s_mul_i32 s1, s1, 8
	s_waitcnt vmcnt(0)
	v_readfirstlane_b32 s0, v3
	s_add_u32 s0, s0, 1
	s_cmp_eq_u32 s0, s1
	s_cbranch_scc0 .Lgb8_pollt
	global_atomic_add v0, v1, s[8:9] offset:256
	s_branch .Lgb8_relg

; #define RUNPH(n) { run_phase(p, (n), smem); grid.sync(); }
; __global__ void __launch_bounds__(256, 2) mega(Params p) {
;   extern __shared__ __attribute__((aligned(16))) char smem[];
;   cg::grid_group grid = cg::this_grid();
;   RUNPH(0) RUNPH(1) RUNPH(2) RUNPH(3) RUNPH(4) RUNPH(5) RUNPH(6) RUNPH(7) RUNPH(8)
;   RUNPH(18) RUNPH(19) RUNPH(9)
.LBB0_466:
	s_or_b64 exec, exec, s[6:7]
	s_waitcnt vmcnt(0)
	s_barrier
	s_mov_b64 s[6:7], exec
	v_readlane_b32 s0, v225, 14
	v_readlane_b32 s1, v225, 15
	s_and_b64 s[0:1], s[6:7], s[0:1]
	s_mov_b64 exec, s[0:1]
	s_cbranch_execz .LBB0_476
	buffer_wbl2 sc1
	s_waitcnt vmcnt(0)
	s_and_b32 s0, s98, 7
	s_sub_u32 s1, s99, s0
	s_add_u32 s1, s1, 7
	s_lshr_b32 s1, s1, 3
	s_mul_i32 s1, s1, 9
	s_lshl_b32 s0, s0, 8
	v_mov_b32_e32 v2, s0
	v_mov_b32_e32 v0, 0
	v_mov_b32_e32 v1, 1
	s_add_u32 s8, s30, 0x3eb38000
	s_addc_u32 s9, s31, 0
	s_mov_b32 s12, 0
	global_atomic_add v3, v2, v1, s[8:9] sc0
	s_waitcnt vmcnt(0)
	v_readfirstlane_b32 s0, v3
	s_add_u32 s0, s0, 1
	s_cmp_eq_u32 s0, s1
	s_cbranch_scc0 .Lgb9_pollg
	s_add_u32 s8, s8, 0x1000
	s_addc_u32 s9, s9, 0
	global_atomic_add v3, v0, v1, s[8:9] sc0
	s_min_u32 s1, s99, 8
	s_mul_i32 s1, s1, 9
	s_waitcnt vmcnt(0)
	v_readfirstlane_b32 s0, v3
	s_add_u32 s0, s0, 1
	s_cmp_eq_u32 s0, s1
	s_cbranch_scc0 .Lgb9_pollt
	global_atomic_add v0, v1, s[8:9] offset:256
	s_branch .Lgb9_relg

; #define RUNPH(n) { run_phase(p, (n), smem); grid.sync(); }
; __global__ void __launch_bounds__(256, 2) mega(Params p) {
;   extern __shared__ __attribute__((aligned(16))) char smem[];
;   cg::grid_group grid = cg::this_grid();
;   RUNPH(0) RUNPH(1) RUNPH(2) RUNPH(3) RUNPH(4) RUNPH(5) RUNPH(6) RUNPH(7) RUNPH(8)
;   RUNPH(18) RUNPH(19) RUNPH(9)
.LBB0_972:
	s_waitcnt vmcnt(0)
	s_barrier
	s_mov_b64 s[6:7], exec
	v_readlane_b32 s0, v225, 14
	v_readlane_b32 s1, v225, 15
	s_and_b64 s[0:1], s[6:7], s[0:1]
	s_mov_b64 exec, s[0:1]
	s_cbranch_execz .LBB0_982
	buffer_wbl2 sc1
	s_waitcnt vmcnt(0)
	s_and_b32 s0, s98, 7
	s_sub_u32 s1, s99, s0
	s_add_u32 s1, s1, 7
	s_lshr_b32 s1, s1, 3
	s_mul_i32 s1, s1, 10
	s_lshl_b32 s0, s0, 8
	v_mov_b32_e32 v2, s0
	v_mov_b32_e32 v0, 0
	v_mov_b32_e32 v1, 1
	s_add_u32 s14, s30, 0x3eb38000
	s_addc_u32 s15, s31, 0
	s_mov_b32 s16, 0
	global_atomic_add v3, v2, v1, s[14:15] sc0
	s_waitcnt vmcnt(0)
	v_readfirstlane_b32 s0, v3
	s_add_u32 s0, s0, 1
	s_cmp_eq_u32 s0, s1
	s_cbranch_scc0 .Lgb10_pollg
	s_add_u32 s14, s14, 0x1000
	s_addc_u32 s15, s15, 0
	global_atomic_add v3, v0, v1, s[14:15] sc0
	s_min_u32 s1, s99, 8
	s_mul_i32 s1, s1, 10
	s_waitcnt vmcnt(0)
	v_readfirstlane_b32 s0, v3
	s_add_u32 s0, s0, 1
	s_cmp_eq_u32 s0, s1
	s_cbranch_scc0 .Lgb10_pollt
	global_atomic_add v0, v1, s[14:15] offset:256
	s_branch .Lgb10_relg

; #define RUNPH(n) { run_phase(p, (n), smem); grid.sync(); }
; __global__ void __launch_bounds__(256, 2) mega(Params p) {
;   extern __shared__ __attribute__((aligned(16))) char smem[];
;   cg::grid_group grid = cg::this_grid();
;   RUNPH(0) RUNPH(1) RUNPH(2) RUNPH(3) RUNPH(4) RUNPH(5) RUNPH(6) RUNPH(7) RUNPH(8)
;   RUNPH(18) RUNPH(19) RUNPH(9)
.LBB0_1481:
	s_waitcnt vmcnt(0)
	s_barrier
	s_mov_b64 s[6:7], exec
	v_readlane_b32 s0, v225, 14
	v_readlane_b32 s1, v225, 15
	v_readlane_b32 s74, v225, 4
	s_and_b64 s[0:1], s[6:7], s[0:1]
	v_readlane_b32 s75, v225, 5
	v_readlane_b32 s92, v225, 16
	s_mov_b64 exec, s[0:1]
	s_cbranch_execz .LBB0_1491
	buffer_wbl2 sc1
	s_waitcnt vmcnt(0)
	s_and_b32 s0, s98, 7
	s_sub_u32 s1, s99, s0
	s_add_u32 s1, s1, 7
	s_lshr_b32 s1, s1, 3
	s_mul_i32 s1, s1, 11
	s_lshl_b32 s0, s0, 8
	v_mov_b32_e32 v2, s0
	v_mov_b32_e32 v0, 0
	v_mov_b32_e32 v1, 1
	s_add_u32 s8, s30, 0x3eb38000
	s_addc_u32 s9, s31, 0
	s_mov_b32 s12, 0
	global_atomic_add v3, v2, v1, s[8:9] sc0
	s_waitcnt vmcnt(0)
	v_readfirstlane_b32 s0, v3
	s_add_u32 s0, s0, 1
	s_cmp_eq_u32 s0, s1
	s_cbranch_scc0 .Lgb11_pollg
	s_add_u32 s8, s8, 0x1000
	s_addc_u32 s9, s9, 0
	global_atomic_add v3, v0, v1, s[8:9] sc0
	s_min_u32 s1, s99, 8
	s_mul_i32 s1, s1, 11
	s_waitcnt vmcnt(0)
	v_readfirstlane_b32 s0, v3
	s_add_u32 s0, s0, 1
	s_cmp_eq_u32 s0, s1
	s_cbranch_scc0 .Lgb11_pollt
	global_atomic_add v0, v1, s[8:9] offset:256
	s_branch .Lgb11_relg

; #define RUNPH(n) { run_phase(p, (n), smem); grid.sync(); }
; __global__ void __launch_bounds__(256, 2) mega(Params p) {
;   extern __shared__ __attribute__((aligned(16))) char smem[];
;   cg::grid_group grid = cg::this_grid();
;   RUNPH(0) RUNPH(1) RUNPH(2) RUNPH(3) RUNPH(4) RUNPH(5) RUNPH(6) RUNPH(7) RUNPH(8)
;   RUNPH(18) RUNPH(19) RUNPH(9)
;   RUNPH(10) RUNPH(11) RUNPH(12) RUNPH(13) RUNPH(14) RUNPH(15) RUNPH(16)
.LBB0_1498:
	s_waitcnt vmcnt(0)
	s_barrier
	s_mov_b64 s[6:7], exec
	v_readlane_b32 s0, v225, 14
	v_readlane_b32 s1, v225, 15
	s_and_b64 s[0:1], s[6:7], s[0:1]
	v_readlane_b32 s96, v225, 2
	v_readlane_b32 s97, v225, 3
	s_mov_b64 exec, s[0:1]
	s_cbranch_execz .LBB0_1508
	buffer_wbl2 sc1
	s_waitcnt vmcnt(0)
	s_and_b32 s0, s98, 7
	s_sub_u32 s1, s99, s0
	s_add_u32 s1, s1, 7
	s_lshr_b32 s1, s1, 3
	s_mul_i32 s1, s1, 12
	s_lshl_b32 s0, s0, 8
	v_mov_b32_e32 v2, s0
	v_mov_b32_e32 v0, 0
	v_mov_b32_e32 v1, 1
	s_add_u32 s8, s30, 0x3eb38000
	s_addc_u32 s9, s31, 0
	s_mov_b32 s12, 0
	global_atomic_add v3, v2, v1, s[8:9] sc0
	s_waitcnt vmcnt(0)
	v_readfirstlane_b32 s0, v3
	s_add_u32 s0, s0, 1
	s_cmp_eq_u32 s0, s1
	s_cbranch_scc0 .Lgb12_pollg
	s_add_u32 s8, s8, 0x1000
	s_addc_u32 s9, s9, 0
	global_atomic_add v3, v0, v1, s[8:9] sc0
	s_min_u32 s1, s99, 8
	s_mul_i32 s1, s1, 12
	s_waitcnt vmcnt(0)
	v_readfirstlane_b32 s0, v3
	s_add_u32 s0, s0, 1
	s_cmp_eq_u32 s0, s1
	s_cbranch_scc0 .Lgb12_pollt
	global_atomic_add v0, v1, s[8:9] offset:256
	s_branch .Lgb12_relg

; #define RUNPH(n) { run_phase(p, (n), smem); grid.sync(); }
; __global__ void __launch_bounds__(256, 2) mega(Params p) {
;   extern __shared__ __attribute__((aligned(16))) char smem[];
;   cg::grid_group grid = cg::this_grid();
;   RUNPH(0) RUNPH(1) RUNPH(2) RUNPH(3) RUNPH(4) RUNPH(5) RUNPH(6) RUNPH(7) RUNPH(8)
;   RUNPH(18) RUNPH(19) RUNPH(9)
;   RUNPH(10) RUNPH(11) RUNPH(12) RUNPH(13) RUNPH(14) RUNPH(15) RUNPH(16)
.LBB0_1550:
	s_waitcnt vmcnt(0)
	s_barrier
	s_mov_b64 s[6:7], exec
	v_readlane_b32 s0, v225, 14
	v_readlane_b32 s1, v225, 15
	s_and_b64 s[0:1], s[6:7], s[0:1]
	s_mov_b64 exec, s[0:1]
	s_cbranch_execz .LBB0_1560
	buffer_wbl2 sc1
	s_waitcnt vmcnt(0)
	s_and_b32 s0, s98, 7
	s_sub_u32 s1, s99, s0
	s_add_u32 s1, s1, 7
	s_lshr_b32 s1, s1, 3
	s_mul_i32 s1, s1, 13
	s_lshl_b32 s0, s0, 8
	v_mov_b32_e32 v2, s0
	v_mov_b32_e32 v0, 0
	v_mov_b32_e32 v1, 1
	s_add_u32 s8, s30, 0x3eb38000
	s_addc_u32 s9, s31, 0
	s_mov_b32 s12, 0
	global_atomic_add v3, v2, v1, s[8:9] sc0
	s_waitcnt vmcnt(0)
	v_readfirstlane_b32 s0, v3
	s_add_u32 s0, s0, 1
	s_cmp_eq_u32 s0, s1
	s_cbranch_scc0 .Lgb13_pollg
	s_add_u32 s8, s8, 0x1000
	s_addc_u32 s9, s9, 0
	global_atomic_add v3, v0, v1, s[8:9] sc0
	s_min_u32 s1, s99, 8
	s_mul_i32 s1, s1, 13
	s_waitcnt vmcnt(0)
	v_readfirstlane_b32 s0, v3
	s_add_u32 s0, s0, 1
	s_cmp_eq_u32 s0, s1
	s_cbranch_scc0 .Lgb13_pollt
	global_atomic_add v0, v1, s[8:9] offset:256
	s_branch .Lgb13_relg

; #define RUNPH(n) { run_phase(p, (n), smem); grid.sync(); }
; __global__ void __launch_bounds__(256, 2) mega(Params p) {
;   extern __shared__ __attribute__((aligned(16))) char smem[];
;   cg::grid_group grid = cg::this_grid();
;   RUNPH(0) RUNPH(1) RUNPH(2) RUNPH(3) RUNPH(4) RUNPH(5) RUNPH(6) RUNPH(7) RUNPH(8)
;   RUNPH(18) RUNPH(19) RUNPH(9)
;   RUNPH(10) RUNPH(11) RUNPH(12) RUNPH(13) RUNPH(14) RUNPH(15) RUNPH(16)
.LBB0_1598:
	s_waitcnt vmcnt(0)
	s_barrier
	s_mov_b64 s[6:7], exec
	v_readlane_b32 s0, v225, 14
	v_readlane_b32 s1, v225, 15
	s_and_b64 s[0:1], s[6:7], s[0:1]
	s_mov_b64 exec, s[0:1]
	s_cbranch_execz .LBB0_1608
	buffer_wbl2 sc1
	s_waitcnt vmcnt(0)
	s_and_b32 s0, s98, 7
	s_sub_u32 s1, s99, s0
	s_add_u32 s1, s1, 7
	s_lshr_b32 s1, s1, 3
	s_mul_i32 s1, s1, 14
	s_lshl_b32 s0, s0, 8
	v_mov_b32_e32 v2, s0
	v_mov_b32_e32 v0, 0
	v_mov_b32_e32 v1, 1
	s_add_u32 s8, s30, 0x3eb38000
	s_addc_u32 s9, s31, 0
	s_mov_b32 s12, 0
	global_atomic_add v3, v2, v1, s[8:9] sc0
	s_waitcnt vmcnt(0)
	v_readfirstlane_b32 s0, v3
	s_add_u32 s0, s0, 1
	s_cmp_eq_u32 s0, s1
	s_cbranch_scc0 .Lgb14_pollg
	s_add_u32 s8, s8, 0x1000
	s_addc_u32 s9, s9, 0
	global_atomic_add v3, v0, v1, s[8:9] sc0
	s_min_u32 s1, s99, 8
	s_mul_i32 s1, s1, 14
	s_waitcnt vmcnt(0)
	v_readfirstlane_b32 s0, v3
	s_add_u32 s0, s0, 1
	s_cmp_eq_u32 s0, s1
	s_cbranch_scc0 .Lgb14_pollt
	global_atomic_add v0, v1, s[8:9] offset:256
	s_branch .Lgb14_relg

; #define RUNPH(n) { run_phase(p, (n), smem); grid.sync(); }
; __global__ void __launch_bounds__(256, 2) mega(Params p) {
;   extern __shared__ __attribute__((aligned(16))) char smem[];
;   cg::grid_group grid = cg::this_grid();
;   RUNPH(0) RUNPH(1) RUNPH(2) RUNPH(3) RUNPH(4) RUNPH(5) RUNPH(6) RUNPH(7) RUNPH(8)
;   RUNPH(18) RUNPH(19) RUNPH(9)
;   RUNPH(10) RUNPH(11) RUNPH(12) RUNPH(13) RUNPH(14) RUNPH(15) RUNPH(16)
.LBB0_1631:
	s_waitcnt vmcnt(0)
	s_barrier
	s_mov_b64 s[6:7], exec
	v_readlane_b32 s0, v225, 14
	v_readlane_b32 s1, v225, 15
	s_and_b64 s[0:1], s[6:7], s[0:1]
	s_mov_b64 exec, s[0:1]
	s_cbranch_execz .LBB0_1641
	buffer_wbl2 sc1
	s_waitcnt vmcnt(0)
	s_and_b32 s0, s98, 7
	s_sub_u32 s1, s99, s0
	s_add_u32 s1, s1, 7
	s_lshr_b32 s1, s1, 3
	s_mul_i32 s1, s1, 15
	s_lshl_b32 s0, s0, 8
	v_mov_b32_e32 v2, s0
	v_mov_b32_e32 v0, 0
	v_mov_b32_e32 v1, 1
	s_add_u32 s8, s30, 0x3eb38000
	s_addc_u32 s9, s31, 0
	s_mov_b32 s12, 0
	global_atomic_add v3, v2, v1, s[8:9] sc0
	s_waitcnt vmcnt(0)
	v_readfirstlane_b32 s0, v3
	s_add_u32 s0, s0, 1
	s_cmp_eq_u32 s0, s1
	s_cbranch_scc0 .Lgb15_pollg
	s_add_u32 s8, s8, 0x1000
	s_addc_u32 s9, s9, 0
	global_atomic_add v3, v0, v1, s[8:9] sc0
	s_min_u32 s1, s99, 8
	s_mul_i32 s1, s1, 15
	s_waitcnt vmcnt(0)
	v_readfirstlane_b32 s0, v3
	s_add_u32 s0, s0, 1
	s_cmp_eq_u32 s0, s1
	s_cbranch_scc0 .Lgb15_pollt
	global_atomic_add v0, v1, s[8:9] offset:256
	s_branch .Lgb15_relg

; #define RUNPH(n) { run_phase(p, (n), smem); grid.sync(); }
; __global__ void __launch_bounds__(256, 2) mega(Params p) {
;   extern __shared__ __attribute__((aligned(16))) char smem[];
;   cg::grid_group grid = cg::this_grid();
;   RUNPH(0) RUNPH(1) RUNPH(2) RUNPH(3) RUNPH(4) RUNPH(5) RUNPH(6) RUNPH(7) RUNPH(8)
;   RUNPH(18) RUNPH(19) RUNPH(9)
;   RUNPH(10) RUNPH(11) RUNPH(12) RUNPH(13) RUNPH(14) RUNPH(15) RUNPH(16)
.LBB0_1644:
	s_waitcnt vmcnt(0)
	s_barrier
	s_mov_b64 s[6:7], exec
	v_readlane_b32 s0, v225, 14
	v_readlane_b32 s1, v225, 15
	s_and_b64 s[0:1], s[6:7], s[0:1]
	s_mov_b64 exec, s[0:1]
	s_cbranch_execz .LBB0_1654
	buffer_wbl2 sc1
	s_waitcnt vmcnt(0)
	s_and_b32 s0, s98, 7
	s_sub_u32 s1, s99, s0
	s_add_u32 s1, s1, 7
	s_lshr_b32 s1, s1, 3
	s_mul_i32 s1, s1, 16
	s_lshl_b32 s0, s0, 8
	v_mov_b32_e32 v2, s0
	v_mov_b32_e32 v0, 0
	v_mov_b32_e32 v1, 1
	s_add_u32 s8, s30, 0x3eb38000
	s_addc_u32 s9, s31, 0
	s_mov_b32 s12, 0
	global_atomic_add v3, v2, v1, s[8:9] sc0
	s_waitcnt vmcnt(0)
	v_readfirstlane_b32 s0, v3
	s_add_u32 s0, s0, 1
	s_cmp_eq_u32 s0, s1
	s_cbranch_scc0 .Lgb16_pollg
	s_add_u32 s8, s8, 0x1000
	s_addc_u32 s9, s9, 0
	global_atomic_add v3, v0, v1, s[8:9] sc0
	s_min_u32 s1, s99, 8
	s_mul_i32 s1, s1, 16
	s_waitcnt vmcnt(0)
	v_readfirstlane_b32 s0, v3
	s_add_u32 s0, s0, 1
	s_cmp_eq_u32 s0, s1
	s_cbranch_scc0 .Lgb16_pollt
	global_atomic_add v0, v1, s[8:9] offset:256
	s_branch .Lgb16_relg

; #define RUNPH(n) { run_phase(p, (n), smem); grid.sync(); }
; __global__ void __launch_bounds__(256, 2) mega(Params p) {
;   extern __shared__ __attribute__((aligned(16))) char smem[];
;   cg::grid_group grid = cg::this_grid();
;   RUNPH(0) RUNPH(1) RUNPH(2) RUNPH(3) RUNPH(4) RUNPH(5) RUNPH(6) RUNPH(7) RUNPH(8)
;   RUNPH(18) RUNPH(19) RUNPH(9)
;   RUNPH(10) RUNPH(11) RUNPH(12) RUNPH(13) RUNPH(14) RUNPH(15) RUNPH(16)
.LBB0_1661:
	s_or_b64 exec, exec, s[6:7]
	s_waitcnt vmcnt(0)
	s_barrier
	s_mov_b64 s[6:7], exec
	v_readlane_b32 s0, v225, 14
	v_readlane_b32 s1, v225, 15
	s_and_b64 s[0:1], s[6:7], s[0:1]
	s_mov_b64 exec, s[0:1]
	s_cbranch_execz .LBB0_1671
	buffer_wbl2 sc1
	s_waitcnt vmcnt(0)
	s_and_b32 s0, s98, 7
	s_sub_u32 s1, s99, s0
	s_add_u32 s1, s1, 7
	s_lshr_b32 s1, s1, 3
	s_mul_i32 s1, s1, 17
	s_lshl_b32 s0, s0, 8
	v_mov_b32_e32 v2, s0
	v_mov_b32_e32 v0, 0
	v_mov_b32_e32 v1, 1
	s_add_u32 s8, s30, 0x3eb38000
	s_addc_u32 s9, s31, 0
	s_mov_b32 s12, 0
	global_atomic_add v3, v2, v1, s[8:9] sc0
	s_waitcnt vmcnt(0)
	v_readfirstlane_b32 s0, v3
	s_add_u32 s0, s0, 1
	s_cmp_eq_u32 s0, s1
	s_cbranch_scc0 .Lgb17_pollg
	s_add_u32 s8, s8, 0x1000
	s_addc_u32 s9, s9, 0
	global_atomic_add v3, v0, v1, s[8:9] sc0
	s_min_u32 s1, s99, 8
	s_mul_i32 s1, s1, 17
	s_waitcnt vmcnt(0)
	v_readfirstlane_b32 s0, v3
	s_add_u32 s0, s0, 1
	s_cmp_eq_u32 s0, s1
	s_cbranch_scc0 .Lgb17_pollt
	global_atomic_add v0, v1, s[8:9] offset:256
	s_branch .Lgb17_relg

; #define RUNPH(n) { run_phase(p, (n), smem); grid.sync(); }
; __global__ void __launch_bounds__(256, 2) mega(Params p) {
;   extern __shared__ __attribute__((aligned(16))) char smem[];
;   cg::grid_group grid = cg::this_grid();
;   RUNPH(0) RUNPH(1) RUNPH(2) RUNPH(3) RUNPH(4) RUNPH(5) RUNPH(6) RUNPH(7) RUNPH(8)
;   RUNPH(18) RUNPH(19) RUNPH(9)
;   RUNPH(10) RUNPH(11) RUNPH(12) RUNPH(13) RUNPH(14) RUNPH(15) RUNPH(16)
.LBB0_1695:
	s_waitcnt vmcnt(0)
	s_barrier
	s_mov_b64 s[6:7], exec
	v_readlane_b32 s0, v225, 14
	v_readlane_b32 s1, v225, 15
	s_and_b64 s[0:1], s[6:7], s[0:1]
	s_mov_b64 exec, s[0:1]
	s_cbranch_execz .LBB0_1705
	buffer_wbl2 sc1
	s_waitcnt vmcnt(0)
	s_and_b32 s0, s98, 7
	s_sub_u32 s1, s99, s0
	s_add_u32 s1, s1, 7
	s_lshr_b32 s1, s1, 3
	s_mul_i32 s1, s1, 18
	s_lshl_b32 s0, s0, 8
	v_mov_b32_e32 v2, s0
	v_mov_b32_e32 v0, 0
	v_mov_b32_e32 v1, 1
	s_add_u32 s2, s30, 0x3eb38000
	s_addc_u32 s3, s31, 0
	s_mov_b32 s8, 0
	global_atomic_add v3, v2, v1, s[2:3] sc0
	s_waitcnt vmcnt(0)
	v_readfirstlane_b32 s0, v3
	s_add_u32 s0, s0, 1
	s_cmp_eq_u32 s0, s1
	s_cbranch_scc0 .Lgb18_pollg
	s_add_u32 s2, s2, 0x1000
	s_addc_u32 s3, s3, 0
	global_atomic_add v3, v0, v1, s[2:3] sc0
	s_min_u32 s1, s99, 8
	s_mul_i32 s1, s1, 18
	s_waitcnt vmcnt(0)
	v_readfirstlane_b32 s0, v3
	s_add_u32 s0, s0, 1
	s_cmp_eq_u32 s0, s1
	s_cbranch_scc0 .Lgb18_pollt
	global_atomic_add v0, v1, s[2:3] offset:256
	s_branch .Lgb18_relg
